# P6 dense attention: anti-phase halves with static priority raise for the leading half (waves 0-3), hand-scheduled tile body, tile loads one iteration ahead; fix-up carry chain batched
# speedup vs baseline: 1.0111x; 1.0029x over previous
; #define A_GLOAD(t) do { _Pragma("unroll") for (int _i = 0; _i < 2; ++_i) { kst[_i] = *(const u32x4*)(kg + (size_t)((t) * 64 + _i * 32) * 512); vst[_i] = *(const u32x4*)(vg + (size_t)((t) * 64 + _i * 32) * 512); } } while (0)
; #define A_LSTORE(buf) do { _Pragma("unroll") for (int _i = 0; _i < 2; ++_i) { *(PG8_LAS u32x4*)(lds + (buf) * A_STAGE + (srow + _i * 32) * A_KP + sch * 16) = kst[_i]; \
;         *(PG8_LAS u32x4*)(lds + (buf) * A_STAGE + A_KBYTES + (srow + _i * 32) * A_VP + sch * 16) = vst[_i]; } } while (0)
; __device__ __forceinline__ void attn_dense_unit(const Params& p, PG8_LAS unsigned char* lds, int b, int n, int qb) {
;     ...
;     const int q = qb * 128 + wave * 16 + (r & 15), head = 2 * n + (r >> 4);
;     const size_t qrow = (size_t)b * SEQ + q;
;     bf16x8 qf[8];
; #pragma unroll
;     for (int ks = 0; ks < 8; ++ks) qf[ks] = *(const bf16x8*)(QB + qrow * 1024 + head * HD + ks * 16 + kh * 8);
;     f32x16 O[4];
; #pragma unroll
;     for (int dt = 0; dt < 4; ++dt)
; #pragma unroll
;         for (int i = 0; i < 16; ++i) O[dt][i] = 0.f;
;     float m = -INFINITY, l = 0.f;
;     const int ntile = 2 * qb + 2, qmax_w = qb * 128 + wave * 16 + 15;
;     const int srow = tid >> 4, sch = tid & 15;
;     const bf16_t* kg = KB + ((size_t)b * SEQ + srow) * 512 + n * HD + sch * 8;
;     const bf16_t* vg = VB + ((size_t)b * SEQ + srow) * 512 + n * HD + sch * 8;
;     u32x4 kst[2], vst[2];
;     ...
;     A_GLOAD(0); A_LSTORE(0);
;     unsigned long long mw = BM[qrow * 64];
;     __syncthreads();
;     const int i16 = lane & 15, g2 = (lane >> 4) & 1;
;     const int vlane_off = (4 * kh + (i16 >> 2)) * A_VP + (16 * g2 + 4 * (i16 & 3)) * 2;
;     for (int t = 0; t < ntile; ++t) {
;         const bool more = (t + 1 < ntile);
;         if (more) A_GLOAD(t + 1);
.LBB0_2873:
	v_mov_b32_e32 v28, v0
	s_lshl_b32 s12, s43, 10
	v_ashrrev_i32_e32 v18, 4, v28
	s_and_b32 s36, s12, 0x1000
	s_mov_b32 s37, s13
	v_ashrrev_i32_e32 v19, 31, v18
	s_waitcnt vmcnt(0)
	v_lshl_add_u64 v[2:3], v[18:19], 0, s[36:37]
	s_lshl_b32 s12, s43, 8
	v_lshlrev_b64 v[2:3], 10, v[2:3]
	s_and_b32 s44, s12, 0x300
	v_lshl_add_u64 v[4:5], s[8:9], 0, v[2:3]
	s_mov_b32 s45, s13
	v_lshl_add_u64 v[2:3], s[6:7], 0, v[2:3]
	v_lshl_add_u64 v[4:5], v[4:5], 0, s[44:45]
	v_lshl_add_u64 v[2:3], v[2:3], 0, s[44:45]
	s_ashr_i32 s45, s43, 3
	v_readfirstlane_b32 s46, v28
	v_and_b32_e32 v22, 15, v28
	s_sub_i32 s12, 31, s45
	s_lshr_b32 s32, s46, 8
	s_ashr_i32 s46, s46, 2
	v_lshlrev_b32_e32 v20, 4, v22
	v_mov_b32_e32 v21, v147
	s_lshl_b32 s12, s12, 7
	s_and_b32 s46, s46, -16
	v_lshl_add_u64 v[10:11], v[4:5], 0, v[20:21]
	s_add_i32 s46, s46, s12
	v_lshl_add_u64 v[12:13], v[2:3], 0, v[20:21]
	global_load_dwordx4 v[2:5], v[10:11], off
	global_load_dwordx4 v[6:9], v[12:13], off
	v_add_co_u32_e32 v10, vcc, s33, v10
	v_or_b32_e32 v22, s46, v22
	s_nop 0
	v_addc_co_u32_e32 v11, vcc, 0, v11, vcc
	v_ashrrev_i32_e32 v23, 31, v22
	v_lshlrev_b32_e32 v26, 3, v28
	v_add_co_u32_e32 v14, vcc, s33, v12
	v_lshl_add_u64 v[148:149], v[22:23], 0, s[36:37]
	v_and_b32_e32 v26, 0x80, v26
	v_addc_co_u32_e32 v15, vcc, 0, v13, vcc
	v_lshlrev_b64 v[24:25], 11, v[148:149]
	v_or_b32_e32 v150, s44, v26
	global_load_dwordx4 v[10:13], v[10:11], off
	s_nop 0
	global_load_dwordx4 v[14:17], v[14:15], off
	v_bfe_u32 v21, v28, 5, 1
	v_lshl_add_u64 v[24:25], s[4:5], 0, v[24:25]
	v_lshlrev_b32_e32 v146, 1, v150
	v_lshl_add_u64 v[24:25], v[24:25], 0, v[146:147]
	v_lshlrev_b32_e32 v146, 4, v21
	v_lshl_add_u64 v[24:25], v[24:25], 0, v[146:147]
	global_load_dwordx4 v[126:129], v[24:25], off
	global_load_dwordx4 v[122:125], v[24:25], off offset:32
	global_load_dwordx4 v[118:121], v[24:25], off offset:64
	global_load_dwordx4 v[114:117], v[24:25], off offset:96
	global_load_dwordx4 v[106:109], v[24:25], off offset:128
	global_load_dwordx4 v[102:105], v[24:25], off offset:160
	v_lshlrev_b64 v[26:27], 9, v[148:149]
	v_lshl_add_u64 v[26:27], s[10:11], 0, v[26:27]
	global_load_dwordx2 v[158:159], v[26:27], off
	global_load_dwordx4 v[110:113], v[24:25], off offset:192
	global_load_dwordx4 v[98:101], v[24:25], off offset:224
	v_lshrrev_b32_e32 v26, 2, v28
	v_mul_lo_u32 v163, v18, s38
	v_lshlrev_b32_e32 v151, 2, v21
	v_add_u32_e32 v165, 0, v20
	v_and_b32_e32 v25, 16, v28
	v_lshlrev_b32_e32 v27, 2, v28
	v_mul_lo_u32 v164, v18, s39
	v_and_or_b32 v21, v26, 3, v151
	v_add_u32_e32 v26, v165, v163
	s_lshl_b32 s12, s3, 9
	v_and_b32_e32 v24, 31, v28
	v_add_u32_e32 v28, v165, v164
	s_and_b32 s12, s12, 0x200000
	s_lshl_b32 s36, s3, 10
	s_and_b32 s44, s42, 3
	s_and_b32 s36, s36, 0x400000
	s_lshl_b32 s47, s44, 8
	v_mul_u32_u24_e32 v161, 0x140, v21
	v_mul_u32_u24_e32 v166, 0x110, v24
	s_lshl_b32 s45, s45, 1
	s_or_b32 s44, s46, 15
	s_sub_i32 s45, 63, s45
	v_mov_b32_e32 v167, 0xff800000
	v_mov_b32_e32 v160, 0
	s_mov_b32 s46, 0
	s_waitcnt vmcnt(0)
	ds_write_b128 v26, v[2:5]
	ds_write_b128 v28, v[6:9] offset:17408
	ds_write_b128 v26, v[10:13] offset:8704
	ds_write_b128 v28, v[14:17] offset:27648
	v_and_or_b32 v2, v27, 12, v25
	v_lshlrev_b32_e32 v162, 1, v2
	v_lshlrev_b64 v[2:3], 9, v[22:23]
	v_lshl_add_u64 v[2:3], v[2:3], 0, s[12:13]
	v_lshl_add_u64 v[152:153], v[2:3], 0, s[14:15]
	v_lshlrev_b64 v[2:3], 10, v[18:19]
	v_lshl_add_u64 v[154:155], s[36:37], 0, v[2:3]
	v_mov_b32_e32 v16, v147
	v_mov_b32_e32 v17, v147
	v_or3_b32 v154, v154, s47, v20
	v_mov_b32_e32 v2, v147
	v_mov_b32_e32 v3, v147
	v_mov_b32_e32 v4, v147
	v_mov_b32_e32 v5, v147
	v_mov_b32_e32 v6, v147
	v_mov_b32_e32 v7, v147
	v_mov_b32_e32 v8, v147
	v_mov_b32_e32 v9, v147
	v_mov_b32_e32 v10, v147
	v_mov_b32_e32 v11, v147
	v_mov_b32_e32 v12, v147
	v_mov_b32_e32 v13, v147
	v_mov_b32_e32 v14, v147
	v_mov_b32_e32 v15, v147
	v_mov_b64_e32 v[32:33], v[16:17]
	v_mov_b64_e32 v[48:49], v[16:17]
	v_mov_b64_e32 v[64:65], v[16:17]
	s_mov_b32 s12, 0
	v_mov_b64_e32 v[30:31], v[14:15]
	v_mov_b64_e32 v[28:29], v[12:13]
	v_mov_b64_e32 v[26:27], v[10:11]
	v_mov_b64_e32 v[24:25], v[8:9]
	v_mov_b64_e32 v[22:23], v[6:7]
	v_mov_b64_e32 v[20:21], v[4:5]
	v_mov_b64_e32 v[18:19], v[2:3]
	v_mov_b64_e32 v[46:47], v[14:15]
	v_mov_b64_e32 v[44:45], v[12:13]
	v_mov_b64_e32 v[42:43], v[10:11]
	v_mov_b64_e32 v[40:41], v[8:9]
	v_mov_b64_e32 v[38:39], v[6:7]
	v_mov_b64_e32 v[36:37], v[4:5]
	v_mov_b64_e32 v[34:35], v[2:3]
	v_mov_b64_e32 v[62:63], v[14:15]
	v_mov_b64_e32 v[60:61], v[12:13]
	v_mov_b64_e32 v[58:59], v[10:11]
	v_mov_b64_e32 v[56:57], v[8:9]
	v_mov_b64_e32 v[54:55], v[6:7]
	v_mov_b64_e32 v[52:53], v[4:5]
	v_mov_b64_e32 v[50:51], v[2:3]
	v_lshl_add_u64 v[66:67], s[34:35], 0, v[154:155]
	v_add_co_u32_e32 v68, vcc, 0x35556000, v66
	s_nop 1
	v_addc_co_u32_e32 v69, vcc, 0, v67, vcc
	global_load_dwordx4 v[130:133], v[68:69], off offset:512
	v_add_co_u32_e32 v68, vcc, 0x35d96000, v66
	s_nop 1
	v_addc_co_u32_e32 v69, vcc, 0, v67, vcc
	global_load_dwordx4 v[134:137], v[68:69], off offset:512
	v_add_co_u32_e32 v68, vcc, 0x3555e000, v66
	s_nop 1
	v_addc_co_u32_e32 v69, vcc, 0, v67, vcc
	global_load_dwordx4 v[138:141], v[68:69], off offset:512
	v_add_co_u32_e32 v68, vcc, 0x35d9e000, v66
	s_nop 1
	v_addc_co_u32_e32 v69, vcc, 0, v67, vcc
	global_load_dwordx4 v[142:145], v[68:69], off offset:512
	s_waitcnt lgkmcnt(0)
	s_barrier
	s_cmp_eq_u32 s32, 0
	s_cbranch_scc1 .Lstg_a
	s_barrier
	s_branch .Lstg_a2
.Lstg_a:
	s_setprio 1
; #define PG8_LAS __attribute__((address_space(3)))
; __device__ __forceinline__ float xhalf_max(float x) { const auto sw = __builtin_amdgcn_permlane32_swap(__float_as_uint(x), __float_as_uint(x), false, false); return fmaxf(__uint_as_float(sw[0]), __uint_as_float(sw[1])); }
; __device__ __forceinline__ void attn_dense_unit(const Params& p, PG8_LAS unsigned char* lds, int b, int n, int qb) {
;     ...
;     for (int t = 0; t < ntile; ++t) {
;         const bool more = (t + 1 < ntile);
;         if (more) A_GLOAD(t + 1);
;         const unsigned long long mw_next = more ? BM[qrow * 64 + t + 1] : 0ull;
;         const int buf = t & 1;
;         if (t * 64 <= qmax_w) {
;             PG8_LAS unsigned char* kb = lds + buf * A_STAGE; PG8_LAS unsigned char* vb = kb + A_KBYTES;
;             f32x16 s0, s1;
; #pragma unroll
;             for (int i = 0; i < 16; ++i) { s0[i] = 0.f; s1[i] = 0.f; }
; #pragma unroll
;             for (int ks = 0; ks < 8; ++ks) {
;                 const bf16x8 k0 = *(const PG8_LAS bf16x8*)(kb + r * A_KP + (ks * 16 + kh * 8) * 2);
;                 const bf16x8 k1 = *(const PG8_LAS bf16x8*)(kb + (32 + r) * A_KP + (ks * 16 + kh * 8) * 2);
;                 s0 = __builtin_amdgcn_mfma_f32_32x32x16_bf16(k0, qf[ks], s0, 0, 0, 0);
;                 s1 = __builtin_amdgcn_mfma_f32_32x32x16_bf16(k1, qf[ks], s1, 0, 0, 0);
;             }
;             const unsigned lo = (unsigned)mw >> (4 * kh), hi = (unsigned)(mw >> 32) >> (4 * kh);
;             float mx = -INFINITY;
; #pragma unroll
;             for (int i = 0; i < 16; ++i) {
;                 const unsigned bit = 1u << ((i & 3) + 8 * (i >> 2));
;                 s0[i] = (lo & bit) ? s0[i] * A_SC : -INFINITY; s1[i] = (hi & bit) ? s1[i] * A_SC : -INFINITY;
;                 mx = fmaxf(mx, fmaxf(s0[i], s1[i]));
;             }
;             mx = xhalf_max(mx);
;             const float m_new = fmaxf(m, mx), m_safe = (m_new == -INFINITY) ? 0.f : m_new;
;             const float alpha = __builtin_amdgcn_exp2f(m - m_safe);
;             float lsum = 0.f;
; #pragma unroll
;             for (int i = 0; i < 16; ++i) { s0[i] = __builtin_amdgcn_exp2f(s0[i] - m_safe); s1[i] = __builtin_amdgcn_exp2f(s1[i] - m_safe); lsum += s0[i] + s1[i]; }
;             l = l * alpha + lsum; m = m_new;
.Lstg_a2:
.LBB0_2874:
	s_and_b32 s47, s46, 1
	s_cmp_gt_i32 s12, s44
	s_cselect_b64 s[36:37], -1, 0
	v_lshl_add_u64 v[66:67], s[34:35], 0, v[152:153]
	global_load_dwordx2 v[156:157], v[66:67], off
	s_and_b64 vcc, exec, s[36:37]
	s_cbranch_vccnz .LBB0_2878
	s_mul_i32 s48, s47, 0x9400
	v_add3_u32 v232, s48, v166, v146
	ds_read_b128 v[168:171], v232
	ds_read_b128 v[172:175], v232 offset:8704
	ds_read_b128 v[176:179], v232 offset:32
	ds_read_b128 v[180:183], v232 offset:8736
	ds_read_b128 v[184:187], v232 offset:64
	ds_read_b128 v[188:191], v232 offset:8768
	ds_read_b128 v[192:195], v232 offset:96
	ds_read_b128 v[196:199], v232 offset:8800
	ds_read_b128 v[200:203], v232 offset:128
	ds_read_b128 v[204:207], v232 offset:8832
	ds_read_b128 v[208:211], v232 offset:160
	ds_read_b128 v[212:215], v232 offset:8864
	v_lshrrev_b32_e32 v158, v151, v158
	v_lshrrev_b32_e32 v159, v151, v159
	v_add3_u32 v233, s48, v161, v162
	s_waitcnt lgkmcnt(11)
	v_mfma_f32_32x32x16_bf16 v[66:81], v[168:171], v[126:129], 0
	s_waitcnt lgkmcnt(10)
	v_mfma_f32_32x32x16_bf16 v[82:97], v[172:175], v[126:129], 0
	ds_read_b128 v[216:219], v232 offset:192
	ds_read_b128 v[220:223], v232 offset:8896
	ds_read_b128 v[224:227], v232 offset:224
	ds_read_b128 v[228:231], v232 offset:8928
	s_waitcnt lgkmcnt(13)
	v_mfma_f32_32x32x16_bf16 v[66:81], v[176:179], v[122:125], v[66:81]
	s_waitcnt lgkmcnt(12)
	v_mfma_f32_32x32x16_bf16 v[82:97], v[180:183], v[122:125], v[82:97]
	s_waitcnt lgkmcnt(11)
	v_mfma_f32_32x32x16_bf16 v[66:81], v[184:187], v[118:121], v[66:81]
	s_waitcnt lgkmcnt(10)
	v_mfma_f32_32x32x16_bf16 v[82:97], v[188:191], v[118:121], v[82:97]
	s_waitcnt lgkmcnt(9)
	v_mfma_f32_32x32x16_bf16 v[66:81], v[192:195], v[114:117], v[66:81]
	s_waitcnt lgkmcnt(8)
	v_mfma_f32_32x32x16_bf16 v[82:97], v[196:199], v[114:117], v[82:97]
	s_waitcnt lgkmcnt(7)
	v_mfma_f32_32x32x16_bf16 v[66:81], v[200:203], v[106:109], v[66:81]
	s_waitcnt lgkmcnt(6)
	v_mfma_f32_32x32x16_bf16 v[82:97], v[204:207], v[106:109], v[82:97]
	s_waitcnt lgkmcnt(5)
	v_mfma_f32_32x32x16_bf16 v[66:81], v[208:211], v[102:105], v[66:81]
	s_waitcnt lgkmcnt(4)
	v_mfma_f32_32x32x16_bf16 v[82:97], v[212:215], v[102:105], v[82:97]
	s_waitcnt lgkmcnt(3)
	v_mfma_f32_32x32x16_bf16 v[66:81], v[216:219], v[110:113], v[66:81]
	s_waitcnt lgkmcnt(2)
	v_mfma_f32_32x32x16_bf16 v[82:97], v[220:223], v[110:113], v[82:97]
	s_waitcnt lgkmcnt(1)
	v_mfma_f32_32x32x16_bf16 v[66:81], v[224:227], v[98:101], v[66:81]
	s_waitcnt lgkmcnt(0)
	v_mfma_f32_32x32x16_bf16 v[82:97], v[228:231], v[98:101], v[82:97]
	ds_read_b64_tr_b16 v[168:169], v233 offset:17408
	ds_read_b64_tr_b16 v[170:171], v233 offset:19968
	ds_read_b64_tr_b16 v[172:173], v233 offset:17472
	ds_read_b64_tr_b16 v[174:175], v233 offset:20032
	ds_read_b64_tr_b16 v[176:177], v233 offset:17536
	ds_read_b64_tr_b16 v[178:179], v233 offset:20096
	ds_read_b64_tr_b16 v[180:181], v233 offset:17600
	ds_read_b64_tr_b16 v[182:183], v233 offset:20160
	v_bfe_i32 v234, v158, 0, 1
	v_bfe_i32 v235, v159, 0, 1
	s_nop 1
	v_bfi_b32 v66, v234, v66, s40
	v_bfe_i32 v234, v158, 1, 1
	v_bfi_b32 v82, v235, v82, s40
	v_bfe_i32 v235, v159, 1, 1
	v_bfi_b32 v67, v234, v67, s40
	v_bfe_i32 v234, v158, 2, 1
	v_bfi_b32 v83, v235, v83, s40
	v_bfe_i32 v235, v159, 2, 1
	v_max_f32_e32 v232, v66, v82
	v_max3_f32 v232, v232, v67, v83
	v_bfi_b32 v68, v234, v68, s40
	v_bfe_i32 v234, v158, 3, 1
	v_bfi_b32 v84, v235, v84, s40
	v_bfe_i32 v235, v159, 3, 1
	v_max3_f32 v232, v232, v68, v84
	v_bfi_b32 v69, v234, v69, s40
	v_bfe_i32 v234, v158, 8, 1
	v_bfi_b32 v85, v235, v85, s40
	v_bfe_i32 v235, v159, 8, 1
	v_max3_f32 v232, v232, v69, v85
	ds_read_b64_tr_b16 v[184:185], v233 offset:22528
	ds_read_b64_tr_b16 v[186:187], v233 offset:25088
	ds_read_b64_tr_b16 v[188:189], v233 offset:22592
	ds_read_b64_tr_b16 v[190:191], v233 offset:25152
	ds_read_b64_tr_b16 v[192:193], v233 offset:22656
	ds_read_b64_tr_b16 v[194:195], v233 offset:25216
	ds_read_b64_tr_b16 v[196:197], v233 offset:22720
	ds_read_b64_tr_b16 v[198:199], v233 offset:25280
	v_bfi_b32 v70, v234, v70, s40
	v_bfe_i32 v234, v158, 9, 1
	v_bfi_b32 v86, v235, v86, s40
	v_bfe_i32 v235, v159, 9, 1
	v_max3_f32 v232, v232, v70, v86
	v_bfi_b32 v71, v234, v71, s40
	v_bfe_i32 v234, v158, 10, 1
	v_bfi_b32 v87, v235, v87, s40
	v_bfe_i32 v235, v159, 10, 1
	v_max3_f32 v232, v232, v71, v87
	v_bfi_b32 v72, v234, v72, s40
	v_bfe_i32 v234, v158, 11, 1
	v_bfi_b32 v88, v235, v88, s40
	v_bfe_i32 v235, v159, 11, 1
	v_max3_f32 v232, v232, v72, v88
	v_bfi_b32 v73, v234, v73, s40
	v_bfe_i32 v234, v158, 16, 1
	v_bfi_b32 v89, v235, v89, s40
	v_bfe_i32 v235, v159, 16, 1
	v_max3_f32 v232, v232, v73, v89
	ds_read_b64_tr_b16 v[200:201], v233 offset:27648
	ds_read_b64_tr_b16 v[202:203], v233 offset:30208
	ds_read_b64_tr_b16 v[204:205], v233 offset:27712
	ds_read_b64_tr_b16 v[206:207], v233 offset:30272
	ds_read_b64_tr_b16 v[208:209], v233 offset:27776
	ds_read_b64_tr_b16 v[210:211], v233 offset:30336
	ds_read_b64_tr_b16 v[212:213], v233 offset:27840
	ds_read_b64_tr_b16 v[214:215], v233 offset:30400
	v_bfi_b32 v74, v234, v74, s40
	v_bfe_i32 v234, v158, 17, 1
	v_bfi_b32 v90, v235, v90, s40
	v_bfe_i32 v235, v159, 17, 1
	v_max3_f32 v232, v232, v74, v90
	v_bfi_b32 v75, v234, v75, s40
	v_bfe_i32 v234, v158, 18, 1
	v_bfi_b32 v91, v235, v91, s40
	v_bfe_i32 v235, v159, 18, 1
	v_max3_f32 v232, v232, v75, v91
	v_bfi_b32 v76, v234, v76, s40
	v_bfe_i32 v234, v158, 19, 1
	v_bfi_b32 v92, v235, v92, s40
	v_bfe_i32 v235, v159, 19, 1
	v_max3_f32 v232, v232, v76, v92
	v_bfi_b32 v77, v234, v77, s40
	v_bfe_i32 v234, v158, 24, 1
	v_bfi_b32 v93, v235, v93, s40
	v_bfe_i32 v235, v159, 24, 1
	v_max3_f32 v232, v232, v77, v93
	ds_read_b64_tr_b16 v[216:217], v233 offset:32768
	ds_read_b64_tr_b16 v[218:219], v233 offset:35328
	ds_read_b64_tr_b16 v[220:221], v233 offset:32832
	ds_read_b64_tr_b16 v[222:223], v233 offset:35392
	ds_read_b64_tr_b16 v[224:225], v233 offset:32896
	ds_read_b64_tr_b16 v[226:227], v233 offset:35456
	ds_read_b64_tr_b16 v[228:229], v233 offset:32960
	ds_read_b64_tr_b16 v[230:231], v233 offset:35520
	v_bfi_b32 v78, v234, v78, s40
	v_bfe_i32 v234, v158, 25, 1
	v_bfi_b32 v94, v235, v94, s40
	v_bfe_i32 v235, v159, 25, 1
	v_max3_f32 v232, v232, v78, v94
	v_bfi_b32 v79, v234, v79, s40
	v_bfe_i32 v234, v158, 26, 1
	v_bfi_b32 v95, v235, v95, s40
	v_bfe_i32 v235, v159, 26, 1
	v_max3_f32 v232, v232, v79, v95
	v_bfi_b32 v80, v234, v80, s40
	v_bfe_i32 v234, v158, 27, 1
	v_bfi_b32 v96, v235, v96, s40
	v_bfe_i32 v235, v159, 27, 1
	v_max3_f32 v232, v232, v80, v96
	v_bfi_b32 v81, v234, v81, s40
	v_bfi_b32 v97, v235, v97, s40
	v_max3_f32 v232, v232, v81, v97
	v_mul_f32_e32 v232, 0x3e0293ee, v232
	v_mov_b32_e32 v158, v232
	s_nop 1
	v_permlane32_swap_b32_e32 v232, v158
	v_max3_f32 v158, v167, v232, v158
	v_cmp_neq_f32_e32 vcc, s40, v158
	s_nop 1
	v_cndmask_b32_e32 v236, 0, v158, vcc
	v_sub_f32_e32 v234, v167, v236
	v_exp_f32_e32 v234, v234
	v_mul_f32_e32 v236, -1.0, v236
	s_cmp_eq_u32 s32, 0
	s_cbranch_scc1 .Lattn_nr_x1
; #define A_GLOAD(t) do { _Pragma("unroll") for (int _i = 0; _i < 2; ++_i) { kst[_i] = *(const u32x4*)(kg + (size_t)((t) * 64 + _i * 32) * 512); vst[_i] = *(const u32x4*)(vg + (size_t)((t) * 64 + _i * 32) * 512); } } while (0)
; #define A_LSTORE(buf) do { _Pragma("unroll") for (int _i = 0; _i < 2; ++_i) { *(PG8_LAS u32x4*)(lds + (buf) * A_STAGE + (srow + _i * 32) * A_KP + sch * 16) = kst[_i]; \
;         *(PG8_LAS u32x4*)(lds + (buf) * A_STAGE + A_KBYTES + (srow + _i * 32) * A_VP + sch * 16) = vst[_i]; } } while (0)
; __device__ __forceinline__ void attn_dense_unit(const Params& p, PG8_LAS unsigned char* lds, int b, int n, int qb) {
;     ...
;     A_GLOAD(0); A_LSTORE(0);
;     unsigned long long mw = BM[qrow * 64];
;     __syncthreads();
;     const int i16 = lane & 15, g2 = (lane >> 4) & 1;
;     const int vlane_off = (4 * kh + (i16 >> 2)) * A_VP + (16 * g2 + 4 * (i16 & 3)) * 2;
;     for (int t = 0; t < ntile; ++t) {
;         const bool more = (t + 1 < ntile);
;         if (more) A_GLOAD(t + 1);
	s_xor_b32 s49, s47, 1
	s_mul_i32 s49, s49, 0x9400
	v_add_u32_e32 v244, s49, v165
	v_add_u32_e32 v245, v244, v163
	v_add_u32_e32 v244, v244, v164
	s_waitcnt vmcnt(4)
	ds_write_b128 v245, v[130:133]
	s_waitcnt vmcnt(3)
	ds_write_b128 v244, v[134:137] offset:17408
	s_waitcnt vmcnt(2)
	ds_write_b128 v245, v[138:141] offset:8704
	s_waitcnt vmcnt(1)
	ds_write_b128 v244, v[142:145] offset:27648
	s_add_i32 s48, s46, 1
	s_cmp_lt_i32 s48, s45
	s_cbranch_scc0 .Lattn_nr_ldy
	v_lshl_add_u64 v[240:241], s[34:35], 0, v[154:155]
	v_add_co_u32_e32 v242, vcc, 0x35566000, v240
	s_nop 1
	v_addc_co_u32_e32 v243, vcc, 0, v241, vcc
	global_load_dwordx4 v[130:133], v[242:243], off offset:512
	v_add_co_u32_e32 v242, vcc, 0x35da6000, v240
	s_nop 1
	v_addc_co_u32_e32 v243, vcc, 0, v241, vcc
	global_load_dwordx4 v[134:137], v[242:243], off offset:512
	v_add_co_u32_e32 v242, vcc, 0x3556e000, v240
	s_nop 1
	v_addc_co_u32_e32 v243, vcc, 0, v241, vcc
	global_load_dwordx4 v[138:141], v[242:243], off offset:512
	v_add_co_u32_e32 v242, vcc, 0x35dae000, v240
	s_nop 1
	v_addc_co_u32_e32 v243, vcc, 0, v241, vcc
	global_load_dwordx4 v[142:145], v[242:243], off offset:512

; #define A_LSTORE(buf) do { _Pragma("unroll") for (int _i = 0; _i < 2; ++_i) { *(PG8_LAS u32x4*)(lds + (buf) * A_STAGE + (srow + _i * 32) * A_KP + sch * 16) = kst[_i]; \
;         *(PG8_LAS u32x4*)(lds + (buf) * A_STAGE + A_KBYTES + (srow + _i * 32) * A_VP + sch * 16) = vst[_i]; } } while (0)
; __device__ __forceinline__ void attn_dense_unit(const Params& p, PG8_LAS unsigned char* lds, int b, int n, int qb) {
;     ...
;             for (int i = 0; i < 16; ++i) { s0[i] = __builtin_amdgcn_exp2f(s0[i] - m_safe); s1[i] = __builtin_amdgcn_exp2f(s1[i] - m_safe); lsum += s0[i] + s1[i]; }
;             l = l * alpha + lsum; m = m_new;
;             if (__ballot(alpha != 1.0f) != 0ull) {
; #pragma unroll
;                 for (int dt = 0; dt < 4; ++dt)
; #pragma unroll
;                     for (int i = 0; i < 16; ++i) O[dt][i] *= alpha;
;             }
;             if (more) A_LSTORE(buf ^ 1);
.Lattn_nr:
	v_fmamk_f32 v67, v67, 0x3e0293ee, v236
	v_exp_f32_e32 v66, v66
	v_fmamk_f32 v83, v83, 0x3e0293ee, v236
	v_exp_f32_e32 v82, v82
	v_fmamk_f32 v68, v68, 0x3e0293ee, v236
	v_exp_f32_e32 v67, v67
	v_fmamk_f32 v84, v84, 0x3e0293ee, v236
	v_exp_f32_e32 v83, v83
	v_fmamk_f32 v69, v69, 0x3e0293ee, v236
	v_exp_f32_e32 v68, v68
	v_fmamk_f32 v85, v85, 0x3e0293ee, v236
	v_exp_f32_e32 v84, v84
	v_fmamk_f32 v70, v70, 0x3e0293ee, v236
	v_exp_f32_e32 v69, v69
	v_fmamk_f32 v86, v86, 0x3e0293ee, v236
	v_exp_f32_e32 v85, v85
	v_fmamk_f32 v71, v71, 0x3e0293ee, v236
	v_exp_f32_e32 v70, v70
	v_fmamk_f32 v87, v87, 0x3e0293ee, v236
	v_exp_f32_e32 v86, v86
	v_fmamk_f32 v72, v72, 0x3e0293ee, v236
	v_exp_f32_e32 v71, v71
	v_fmamk_f32 v88, v88, 0x3e0293ee, v236
	v_exp_f32_e32 v87, v87
	v_fmamk_f32 v73, v73, 0x3e0293ee, v236
	v_exp_f32_e32 v72, v72
	v_fmamk_f32 v89, v89, 0x3e0293ee, v236
	v_exp_f32_e32 v88, v88
	v_fmamk_f32 v74, v74, 0x3e0293ee, v236
	v_exp_f32_e32 v73, v73
	v_fmamk_f32 v90, v90, 0x3e0293ee, v236
	v_exp_f32_e32 v89, v89
	v_fmamk_f32 v75, v75, 0x3e0293ee, v236
	v_exp_f32_e32 v74, v74
	v_fmamk_f32 v91, v91, 0x3e0293ee, v236
	v_exp_f32_e32 v90, v90
	v_fmamk_f32 v76, v76, 0x3e0293ee, v236
	v_exp_f32_e32 v75, v75
	v_fmamk_f32 v92, v92, 0x3e0293ee, v236
	v_exp_f32_e32 v91, v91
	v_fmamk_f32 v77, v77, 0x3e0293ee, v236
	v_exp_f32_e32 v76, v76
	v_fmamk_f32 v93, v93, 0x3e0293ee, v236
	v_exp_f32_e32 v92, v92
	v_fmamk_f32 v78, v78, 0x3e0293ee, v236
	v_exp_f32_e32 v77, v77
	v_fmamk_f32 v94, v94, 0x3e0293ee, v236
	v_exp_f32_e32 v93, v93
	v_fmamk_f32 v79, v79, 0x3e0293ee, v236
	v_exp_f32_e32 v78, v78
	v_fmamk_f32 v95, v95, 0x3e0293ee, v236
	v_exp_f32_e32 v94, v94
	v_fmamk_f32 v80, v80, 0x3e0293ee, v236
	v_exp_f32_e32 v79, v79
	v_fmamk_f32 v96, v96, 0x3e0293ee, v236
	v_exp_f32_e32 v95, v95
	v_fmamk_f32 v81, v81, 0x3e0293ee, v236
	v_exp_f32_e32 v80, v80
	v_fmamk_f32 v97, v97, 0x3e0293ee, v236
	v_exp_f32_e32 v96, v96
	v_exp_f32_e32 v81, v81
	v_exp_f32_e32 v97, v97
	s_cmp_lg_u32 s32, 0
	s_cbranch_scc1 .Lattn_nr_y2
	s_xor_b32 s49, s47, 1
	s_mul_i32 s49, s49, 0x9400
	v_add_u32_e32 v232, s49, v165
	v_add_u32_e32 v235, v232, v163
	v_add_u32_e32 v232, v232, v164
	s_waitcnt vmcnt(4)
	ds_write_b128 v235, v[130:133]
	s_waitcnt vmcnt(3)
	ds_write_b128 v232, v[134:137] offset:17408
	s_waitcnt vmcnt(2)
	ds_write_b128 v235, v[138:141] offset:8704
	s_waitcnt vmcnt(1)
	ds_write_b128 v232, v[142:145] offset:27648
	s_add_i32 s48, s46, 1
	s_cmp_lt_i32 s48, s45
	s_cbranch_scc0 .Lattn_nr_ld
	v_lshl_add_u64 v[232:233], s[34:35], 0, v[154:155]
	v_add_co_u32_e32 v236, vcc, 0x35566000, v232
	s_nop 1
	v_addc_co_u32_e32 v237, vcc, 0, v233, vcc
	global_load_dwordx4 v[130:133], v[236:237], off offset:512
	v_add_co_u32_e32 v236, vcc, 0x35da6000, v232
	s_nop 1
	v_addc_co_u32_e32 v237, vcc, 0, v233, vcc
	global_load_dwordx4 v[134:137], v[236:237], off offset:512
	v_add_co_u32_e32 v236, vcc, 0x3556e000, v232
	s_nop 1
	v_addc_co_u32_e32 v237, vcc, 0, v233, vcc
	global_load_dwordx4 v[138:141], v[236:237], off offset:512
	v_add_co_u32_e32 v236, vcc, 0x35dae000, v232
	s_nop 1
	v_addc_co_u32_e32 v237, vcc, 0, v233, vcc
	global_load_dwordx4 v[142:145], v[236:237], off offset:512
; #define PG8_LAS __attribute__((address_space(3)))
; __device__ __forceinline__ unsigned cvt_pk_bf16(float lo, float hi) { unsigned r; asm volatile("v_cvt_pk_bf16_f32 %0, %1, %2" : "=v"(r) : "v"(lo), "v"(hi)); return r; }
; __device__ __forceinline__ unsigned cvt_pk_bf16(float lo, float hi) { unsigned r; asm volatile("v_cvt_pk_bf16_f32 %0, %1, %2" : "=v"(r) : "v"(lo), "v"(hi)); return r; }
; #define A_LSTORE(buf) do { _Pragma("unroll") for (int _i = 0; _i < 2; ++_i) { *(PG8_LAS u32x4*)(lds + (buf) * A_STAGE + (srow + _i * 32) * A_KP + sch * 16) = kst[_i]; \
;         *(PG8_LAS u32x4*)(lds + (buf) * A_STAGE + A_KBYTES + (srow + _i * 32) * A_VP + sch * 16) = vst[_i]; } } while (0)
; __device__ __forceinline__ void attn_dense_unit(const Params& p, PG8_LAS unsigned char* lds, int b, int n, int qb) {
;     ...
;             bf16x8 pf[2][2];
; #pragma unroll
;             for (int sx = 0; sx < 2; ++sx) {
;                 u32x4 w0, w1;
;                 w0.x = cvt_pk_bf16(s0[8 * sx], s0[8 * sx + 1]); w0.y = cvt_pk_bf16(s0[8 * sx + 2], s0[8 * sx + 3]); w0.z = cvt_pk_bf16(s0[8 * sx + 4], s0[8 * sx + 5]); w0.w = cvt_pk_bf16(s0[8 * sx + 6], s0[8 * sx + 7]);
;                 w1.x = cvt_pk_bf16(s1[8 * sx], s1[8 * sx + 1]); w1.y = cvt_pk_bf16(s1[8 * sx + 2], s1[8 * sx + 3]); w1.z = cvt_pk_bf16(s1[8 * sx + 4], s1[8 * sx + 5]); w1.w = cvt_pk_bf16(s1[8 * sx + 6], s1[8 * sx + 7]);
;                 pf[0][sx] = __builtin_bit_cast(bf16x8, w0); pf[1][sx] = __builtin_bit_cast(bf16x8, w1);
;             }
; #pragma unroll
;             for (int st = 0; st < 2; ++st)
; #pragma unroll
;                 for (int sx = 0; sx < 2; ++sx)
; #pragma unroll
;                     for (int dt = 0; dt < 4; ++dt) {
;                         PG8_LAS unsigned char* a = vb + vlane_off + (st * 32 + 16 * sx) * A_VP + dt * 64;
;                         const s16x4 vlo = __builtin_amdgcn_ds_read_tr16_b64_v4i16((PG8_LAS s16x4*)a);
;                         const s16x4 vhi = __builtin_amdgcn_ds_read_tr16_b64_v4i16((PG8_LAS s16x4*)(a + 8 * A_VP));
;                         const bf16x8 vf = __builtin_shufflevector(vlo, vhi, 0, 1, 2, 3, 4, 5, 6, 7);
;                         O[dt] = __builtin_amdgcn_mfma_f32_32x32x16_bf16(vf, pf[st][sx], O[dt], 0, 0, 0);
;                     }
;         }
;         if (more && !(t * 64 <= qmax_w)) A_LSTORE(buf ^ 1);
;         __syncthreads();
;         mw = mw_next;
;     }
.Lattn_nr_ld:
.Lattn_nr_y2:
	v_cvt_pk_bf16_f32 v240, v66, v67
	v_cvt_pk_bf16_f32 v241, v68, v69
	v_cvt_pk_bf16_f32 v242, v70, v71
	v_cvt_pk_bf16_f32 v243, v72, v73
	v_cvt_pk_bf16_f32 v244, v74, v75
	v_cvt_pk_bf16_f32 v245, v76, v77
	v_cvt_pk_bf16_f32 v246, v78, v79
	v_cvt_pk_bf16_f32 v247, v80, v81
	v_cvt_pk_bf16_f32 v248, v82, v83
	v_cvt_pk_bf16_f32 v249, v84, v85
	v_cvt_pk_bf16_f32 v250, v86, v87
	v_cvt_pk_bf16_f32 v251, v88, v89
	v_cvt_pk_bf16_f32 v252, v90, v91
	v_cvt_pk_bf16_f32 v253, v92, v93
	v_cvt_pk_bf16_f32 v254, v94, v95
	v_cvt_pk_bf16_f32 v255, v96, v97
	s_waitcnt lgkmcnt(4)
	v_mfma_f32_32x32x16_bf16 v[50:65], v[168:171], v[240:243], v[50:65]
	v_add_f32_e32 v159, v67, v83
	v_add_f32_e32 v235, v66, v82
	v_mfma_f32_32x32x16_bf16 v[34:49], v[172:175], v[240:243], v[34:49]
	v_add_f32_e32 v159, v159, v235
	v_add_f32_e32 v235, v68, v84
	v_mfma_f32_32x32x16_bf16 v[18:33], v[176:179], v[240:243], v[18:33]
	v_add_f32_e32 v159, v235, v159
	v_add_f32_e32 v235, v69, v85
	v_mfma_f32_32x32x16_bf16 v[2:17], v[180:183], v[240:243], v[2:17]
	v_add_f32_e32 v159, v235, v159
	v_add_f32_e32 v235, v70, v86
	v_mfma_f32_32x32x16_bf16 v[50:65], v[184:187], v[244:247], v[50:65]
	v_add_f32_e32 v159, v235, v159
	v_add_f32_e32 v235, v71, v87
	v_mfma_f32_32x32x16_bf16 v[34:49], v[188:191], v[244:247], v[34:49]
	v_add_f32_e32 v159, v235, v159
	v_add_f32_e32 v235, v72, v88
	v_mfma_f32_32x32x16_bf16 v[18:33], v[192:195], v[244:247], v[18:33]
	v_add_f32_e32 v159, v235, v159
	v_add_f32_e32 v235, v73, v89
	v_mfma_f32_32x32x16_bf16 v[2:17], v[196:199], v[244:247], v[2:17]
	v_add_f32_e32 v159, v235, v159
	v_add_f32_e32 v235, v74, v90
	v_mfma_f32_32x32x16_bf16 v[50:65], v[200:203], v[248:251], v[50:65]
	v_add_f32_e32 v159, v235, v159
	v_add_f32_e32 v235, v75, v91
	v_mfma_f32_32x32x16_bf16 v[34:49], v[204:207], v[248:251], v[34:49]
	v_add_f32_e32 v159, v235, v159
	v_add_f32_e32 v235, v76, v92
	v_mfma_f32_32x32x16_bf16 v[18:33], v[208:211], v[248:251], v[18:33]
	v_add_f32_e32 v159, v235, v159
	v_add_f32_e32 v235, v77, v93
	v_mfma_f32_32x32x16_bf16 v[2:17], v[212:215], v[248:251], v[2:17]
	v_add_f32_e32 v159, v235, v159
	v_add_f32_e32 v235, v78, v94
	v_mfma_f32_32x32x16_bf16 v[50:65], v[216:219], v[252:255], v[50:65]
	v_add_f32_e32 v159, v235, v159
	v_add_f32_e32 v235, v79, v95
	v_mfma_f32_32x32x16_bf16 v[34:49], v[220:223], v[252:255], v[34:49]
	v_add_f32_e32 v159, v235, v159
	v_add_f32_e32 v235, v80, v96
	v_mfma_f32_32x32x16_bf16 v[18:33], v[224:227], v[252:255], v[18:33]
	v_add_f32_e32 v159, v235, v159
	v_add_f32_e32 v235, v81, v97
	v_mfma_f32_32x32x16_bf16 v[2:17], v[228:231], v[252:255], v[2:17]
	v_add_f32_e32 v159, v235, v159
	v_fmac_f32_e32 v159, v160, v234
	v_mov_b32_e32 v160, v159
	s_andn2_b64 vcc, exec, s[36:37]
	s_cbranch_vccz .LBB0_2879
	s_branch .LBB0_2880
.LBB0_2878:
	v_mov_b32_e32 v158, v167
	s_cmp_eq_u32 s32, 0
	s_cbranch_scc1 .Lstg_c1
	s_xor_b32 s36, s47, 1
	s_mul_i32 s36, s36, 0x9400
	v_add_u32_e32 v66, s36, v165
	v_add_u32_e32 v67, v66, v163
	v_add_u32_e32 v66, v66, v164
	s_waitcnt vmcnt(4)
	ds_write_b128 v67, v[130:133]
	s_waitcnt vmcnt(3)
	ds_write_b128 v66, v[134:137] offset:17408
	s_waitcnt vmcnt(2)
	ds_write_b128 v67, v[138:141] offset:8704
	s_waitcnt vmcnt(1)
	ds_write_b128 v66, v[142:145] offset:27648
	s_add_i32 s48, s46, 1
	s_cmp_lt_i32 s48, s45
	s_cbranch_scc0 .Lattn_skip_ldy
	v_lshl_add_u64 v[66:67], s[34:35], 0, v[154:155]
	v_add_co_u32_e32 v68, vcc, 0x35566000, v66
	s_nop 1
	v_addc_co_u32_e32 v69, vcc, 0, v67, vcc
	global_load_dwordx4 v[130:133], v[68:69], off offset:512
	v_add_co_u32_e32 v68, vcc, 0x35da6000, v66
	s_nop 1
	v_addc_co_u32_e32 v69, vcc, 0, v67, vcc
	global_load_dwordx4 v[134:137], v[68:69], off offset:512
	v_add_co_u32_e32 v68, vcc, 0x3556e000, v66
	s_nop 1
	v_addc_co_u32_e32 v69, vcc, 0, v67, vcc
	global_load_dwordx4 v[138:141], v[68:69], off offset:512
	v_add_co_u32_e32 v68, vcc, 0x35dae000, v66
	s_nop 1
	v_addc_co_u32_e32 v69, vcc, 0, v67, vcc
	global_load_dwordx4 v[142:145], v[68:69], off offset:512

; __device__ __forceinline__ float xhalf_sum(float x) { const auto sw = __builtin_amdgcn_permlane32_swap(__float_as_uint(x), __float_as_uint(x), false, false); return __uint_as_float(sw[0]) + __uint_as_float(sw[1]); }
; __device__ __forceinline__ void attn_dense_unit(const Params& p, PG8_LAS unsigned char* lds, int b, int n, int qb) {
;     ...
;         __syncthreads();
;         mw = mw_next;
;     }
;     ...
;     const float inv = 1.0f / xhalf_sum(l);
.LBB0_2882:
	s_setprio 0
	s_cmp_lg_u32 s32, 0
	s_cbranch_scc1 .Lstg_d
	s_barrier

; __global__ void __launch_bounds__(NTHREADS, 2) mk_fwd(Params p) {
;     extern __shared__ __attribute__((aligned(16))) unsigned char lds_raw[];
	.amdhsa_kernel _ZN12_GLOBAL__N_16mk_fwdENS_6ParamsE
		.amdhsa_group_segment_fixed_size 0
		.amdhsa_private_segment_fixed_size 0
		.amdhsa_kernarg_size 504
		.amdhsa_user_sgpr_count 2
		.amdhsa_user_sgpr_dispatch_ptr 0
		.amdhsa_user_sgpr_queue_ptr 0
		.amdhsa_user_sgpr_kernarg_segment_ptr 1
		.amdhsa_user_sgpr_dispatch_id 0
		.amdhsa_user_sgpr_kernarg_preload_length 0
		.amdhsa_user_sgpr_kernarg_preload_offset 0
		.amdhsa_user_sgpr_private_segment_size 0
		.amdhsa_uses_dynamic_stack 0
		.amdhsa_enable_private_segment 0
		.amdhsa_system_sgpr_workgroup_id_x 1
		.amdhsa_system_sgpr_workgroup_id_y 0
		.amdhsa_system_sgpr_workgroup_id_z 0
		.amdhsa_system_sgpr_workgroup_info 0
		.amdhsa_system_vgpr_workitem_id 0
		.amdhsa_next_free_vgpr 256
		.amdhsa_next_free_sgpr 98
		.amdhsa_accum_offset 256
		.amdhsa_reserve_vcc 1
		.amdhsa_float_round_mode_32 0
		.amdhsa_float_round_mode_16_64 0
		.amdhsa_float_denorm_mode_32 3
		.amdhsa_float_denorm_mode_16_64 3
		.amdhsa_dx10_clamp 1
		.amdhsa_ieee_mode 1
		.amdhsa_fp16_overflow 0
		.amdhsa_tg_split 0
		.amdhsa_exception_fp_ieee_invalid_op 0
		.amdhsa_exception_fp_denorm_src 0
		.amdhsa_exception_fp_ieee_div_zero 0
		.amdhsa_exception_fp_ieee_overflow 0
		.amdhsa_exception_fp_ieee_underflow 0
		.amdhsa_exception_fp_ieee_inexact 0
		.amdhsa_exception_int_div_zero 0
	.end_amdhsa_kernel

; __global__ void __launch_bounds__(NTHREADS, 2) mk_fwd(Params p) {
;     extern __shared__ __attribute__((aligned(16))) unsigned char lds_raw[];
amdhsa.kernels:
  - .agpr_count:     0
    .args:
      - .offset:         0
        .size:           248
        .value_kind:     by_value
      - .offset:         248
        .size:           4
        .value_kind:     hidden_block_count_x
      - .offset:         252
        .size:           4
        .value_kind:     hidden_block_count_y
      - .offset:         256
        .size:           4
        .value_kind:     hidden_block_count_z
      - .offset:         260
        .size:           2
        .value_kind:     hidden_group_size_x
      - .offset:         262
        .size:           2
        .value_kind:     hidden_group_size_y
      - .offset:         264
        .size:           2
        .value_kind:     hidden_group_size_z
      - .offset:         266
        .size:           2
        .value_kind:     hidden_remainder_x
      - .offset:         268
        .size:           2
        .value_kind:     hidden_remainder_y
      - .offset:         270
        .size:           2
        .value_kind:     hidden_remainder_z
      - .offset:         288
        .size:           8
        .value_kind:     hidden_global_offset_x
      - .offset:         296
        .size:           8
        .value_kind:     hidden_global_offset_y
      - .offset:         304
        .size:           8
        .value_kind:     hidden_global_offset_z
      - .offset:         312
        .size:           2
        .value_kind:     hidden_grid_dims
      - .offset:         368
        .size:           4
        .value_kind:     hidden_dynamic_lds_size
    .group_segment_fixed_size: 0
    .kernarg_segment_align: 8
    .kernarg_segment_size: 504
    .language:       OpenCL C
    .language_version:
      - 2
      - 0
    .max_flat_workgroup_size: 512
    .name:           _ZN12_GLOBAL__N_16mk_fwdENS_6ParamsE
    .private_segment_fixed_size: 0
    .sgpr_count:     104
    .sgpr_spill_count: 91
    .symbol:         _ZN12_GLOBAL__N_16mk_fwdENS_6ParamsE.kd
    .uniform_work_group_size: 1
    .uses_dynamic_stack: false
    .vgpr_count:     256
    .vgpr_spill_count: 0
    .wavefront_size: 64
